# v110 plus odd-XCD 1.4 us start stagger at the LRU phase
# baseline (speedup 1.0000x reference)
; DI void phase_lru(const Params& p, unsigned char* shm) {
;     int nbp = -1; LruPar par;
;     for (int it = blockIdx.x; it < 2048; it += gridDim.x) { const int nb = it & 15; if (nb != nbp) { par = lru_params(p, nb); nbp = nb; } lru_tile(p, shm, it >> 4, nb, par); }
;     __syncthreads();
; }
; DI void phase_att(const Params& p, unsigned char* shm) {
;     const int wid = __builtin_amdgcn_readfirstlane(threadIdx.x >> 6);
;     const bf16_t* Z = (const bf16_t*)(p.ws + WS_ZQKV); const bf16_t* GA = (const bf16_t*)(p.ws + WS_ZGA); bf16_t* YB = (bf16_t*)(p.ws + WS_YB);
;     for (int it = blockIdx.x; it < 1024; it += gridDim.x) {
;         const int hp = it & 1, g = (it >> 1) & 3, n = it >> 3;
;         const int head = g * 4 + hp * 2 + (wid >> 2), qw = 32 * (wid & 3);
;         const int kfirst = n == 0 ? 0 : (n - 1) * 128, NT = (n == 0 || n == 127) ? 4 : 6, kt0 = kfirst - n * 128;
;         __syncthreads();
;         const size_t go = (size_t)(n * 128 + qw) * 2048 + head * 128;
;         att::attn_item(Z + (size_t)(n * 128 + qw) * 3072 + head * 128, Z + (size_t)kfirst * 3072 + 2048 + g * 128, Z + (size_t)kfirst * 3072 + 2560 + g * 128,
;                        GA + go, YB + go, NT, kt0, qw, p.in[10][head], (char*)shm);
;     }
;     __syncthreads();
; }
; DI void phase_mixers(const Params& p, unsigned char* shm) { if (p.mix_mask & 1) phase_lru(p, shm); if (p.mix_mask & 2) phase_att(p, shm); }
.LBB0_207:
	s_waitcnt lgkmcnt(0)
	s_cmp_lt_i32 s4, 3
	s_cselect_b64 s[6:7], -1, 0
	s_cmp_gt_i32 s5, 2
	s_cselect_b64 s[4:5], -1, 0
	s_and_b64 s[4:5], s[6:7], s[4:5]
	s_andn2_b64 vcc, exec, s[4:5]
	s_cbranch_vccnz .LBB0_266
	s_load_dword s4, s[0:1], 0xd0
	s_waitcnt lgkmcnt(0)
	s_bitcmp0_b32 s4, 0
	s_cbranch_scc1 .LBB0_234
	s_cmpk_gt_i32 s2, 0x7ff
	s_cbranch_scc1 .LBB0_233
	s_load_dwordx4 s[12:15], s[0:1], 0x40
	s_load_dwordx4 s[16:19], s[0:1], 0x78
	s_load_dwordx4 s[20:23], s[0:1], 0x18
	s_load_dwordx2 s[30:31], s[0:1], 0x30
	s_waitcnt vmcnt(0)
	v_lshrrev_b32_e32 v0, 2, v202
	v_and_b32_e32 v1, 15, v202
	s_movk_i32 s4, 0xf0
	s_waitcnt lgkmcnt(0)
	s_add_u32 s37, s18, 0x1ba00000
	s_addc_u32 s41, s19, 0
	s_add_u32 s34, s18, 0x1c000000
	s_addc_u32 s35, s19, 0
	s_add_u32 s43, s16, 0x4000000
	v_mov_b32_e32 v69, 0
	v_and_or_b32 v71, v0, s4, v1
	s_addc_u32 s45, s17, 0
	s_mov_b32 s70, -1
	s_mov_b32 s36, 0xbfb8aa3b
	s_mov_b32 s47, 0x42ce8ed0
	s_mov_b32 s39, 0
	s_mov_b32 s49, 0xc2b17218
	s_mov_b32 s51, 0x7f800000
	s_movk_i32 s62, 0x2000
	s_mov_b32 s63, 0x3f2aaaab
	s_mov_b32 s40, 0x3e9b6dac
	s_mov_b32 s42, 0x3f2aaada
	s_mov_b32 s44, 0x3f317218
	s_mov_b32 s46, 0xb102e308
	s_mov_b32 s64, 0x33800000
	s_mov_b32 s48, 0xc1000000
	s_mov_b32 s50, 0x3fb8aa3b
	s_mov_b64 s[52:53], 0x2000
	s_mov_b64 s[54:55], 0x4000
	s_movk_i32 s65, 0x4000
	s_mov_b64 s[56:57], 0x6000
	s_movk_i32 s66, 0x6000
	s_movk_i32 s67, 0x110
	s_add_i32 s68, 0, 0x11000
	v_mov_b32_e32 v73, 0x7f800000
	v_mov_b32_e32 v70, 0x3ecc95a3
	s_mov_b32 s69, s2
	v_mov_b32_e32 v180, 0
	v_mov_b32_e32 v162, 0
	v_mov_b32_e32 v91, 0
	v_mov_b32_e32 v89, 0
	v_mov_b32_e32 v85, 0
	v_mov_b32_e32 v81, 0
	v_mov_b32_e32 v79, 0
	v_mov_b32_e32 v77, 0
	v_mov_b32_e32 v90, v69
	v_mov_b32_e32 v88, v69
	v_mov_b32_e32 v84, v69
	v_mov_b32_e32 v80, v69
	v_mov_b32_e32 v78, v69
	v_mov_b32_e32 v76, v69
	v_mov_b32_e32 v74, v69
	v_mov_b32_e32 v72, v69
	s_bitcmp1_b32 s2, 0
	s_cbranch_scc0 .Llru_nostag
	s_sleep 38
